# mlstm_a: V and K tile loads issued at item-loop top (were 3 serialized round trips), on top of the mlstm_c load hoist
# speedup vs baseline: 1.0082x; 1.0047x over previous
; __device__ __forceinline__ float logsigmoidf_(float x) { return fminf(x, 0.f) - log1pf(__expf(-fabsf(x))); }
; __device__ __forceinline__ void phase_mlstm_a(const Args& a, unsigned char* lds) {
;     ...
;     for (int item = blockIdx.x; item < 4096; item += gridDim.x) {
;         const int c = item & 127, h = (item >> 7) & 3, b = item >> 9;
;         const size_t r0 = (size_t)b * SEQ + c * 64;
;         if (wave == 0) {
;             const float ig = SM[(r0 + lane) * 16 + 8 + h] + a.in[I_BI][h];
;             const float lf = logsigmoidf_(SM[(r0 + lane) * 16 + 12 + h] + a.in[I_BF][h]);
;             const float bs = wave_incl_sum(lf, lane);
;             const float bl = __shfl(bs, 63);
;             const float wk = bl - bs + ig;
;             const float ml = wave_max(wk);
;             WS_[lane] = __expf(wk - ml);
;             if (lane == 0) { ML[item] = ml; BL[item] = bl; }
;         }
.LBB0_656:
	s_ashr_i32 s16, s14, 9
	s_ashr_i32 s17, s16, 31
	s_lshl_b32 s60, s14, 6
	s_lshl_b64 s[18:19], s[16:17], 13
	s_and_b32 s10, s60, 0x1fc0
	s_bfe_u32 s61, s14, 0x20007
	s_or_b32 s16, s18, s10
	s_mov_b32 s17, s19
	s_lshr_b32 s10, s14, 7
	s_and_b32 s15, s27, 0x1fc0
	s_and_b32 s10, s10, 3
	s_add_u32 s18, s15, s18
	s_addc_u32 s19, 0, s19
	v_lshl_add_u64 v[252:253], s[18:19], 0, v[16:17]
	v_mad_u64_u32 v[250:251], vcc, v252, s42, 0
	v_mad_i32_i24 v253, v253, s42, v251
	v_lshl_or_b32 v252, s10, 8, v250
	v_lshl_add_u64 v[252:253], v[2:3], 0, v[252:253]
	s_lshl_b32 s10, s61, 7
	global_load_dwordx4 v[228:231], v[252:253], off
	s_nop 0
	v_lshl_add_u64 v[252:253], v[252:253], 0, s[12:13]
	global_load_dwordx4 v[232:235], v[252:253], off
	s_nop 0
	v_lshl_add_u64 v[252:253], s[16:17], 0, v[128:129]
	v_lshlrev_b64 v[252:253], 10, v[252:253]
	v_lshl_add_u64 v[252:253], s[70:71], 0, v[252:253]
	v_lshl_add_u64 v[252:253], v[252:253], 0, s[10:11]
	v_lshlrev_b32_e32 v250, 1, v146
	v_mov_b32_e32 v251, v1
	v_lshl_add_u64 v[252:253], v[252:253], 0, v[250:251]
	v_add_co_u32_e32 v252, vcc, 0x3c000000, v252
	s_nop 1
	v_addc_co_u32_e32 v253, vcc, 0, v253, vcc
	global_load_dwordx4 v[236:239], v[252:253], off offset:512
	s_and_saveexec_b64 s[20:21], s[4:5]
	s_cbranch_execz .LBB0_659
	v_mov_b32_e32 v5, s17
	v_or_b32_e32 v4, s16, v156
	v_lshlrev_b64 v[4:5], 6, v[4:5]
	v_lshl_add_u64 v[4:5], s[58:59], 0, v[4:5]
	s_lshl_b32 s10, s61, 2
	v_lshl_add_u64 v[4:5], v[4:5], 0, s[10:11]
	v_mov_b32_e32 v0, s10
	global_load_dword v37, v[4:5], off offset:48
	global_load_dword v39, v0, s[50:51]
	global_load_dword v38, v0, s[48:49]
	s_nop 0
	global_load_dword v4, v[4:5], off offset:32
	s_waitcnt vmcnt(2)
	v_add_f32_e32 v0, v37, v39
	v_mul_f32_e64 v5, |v0|, s29
	v_exp_f32_e32 v5, v5
	v_min_f32_e32 v0, 0, v0
	v_mov_b32_e32 v37, 0
	v_mov_b32_e32 v39, 0
	v_add_f32_e32 v42, 1.0, v5
	v_add_f32_e32 v43, -1.0, v42
	v_frexp_mant_f32_e32 v44, v42
	v_cvt_f64_f32_e32 v[40:41], v42
	v_sub_f32_e32 v45, v43, v42
	v_frexp_exp_i32_f64_e32 v40, v[40:41]
	v_cmp_gt_f32_e32 vcc, s38, v44
	v_sub_f32_e32 v43, v5, v43
	v_add_f32_e32 v41, 1.0, v45
	v_subbrev_co_u32_e32 v40, vcc, 0, v40, vcc
	v_add_f32_e32 v41, v43, v41
	v_sub_u32_e32 v43, 0, v40
	v_cvt_f32_i32_e32 v40, v40
	v_ldexp_f32 v42, v42, v43
	v_ldexp_f32 v41, v41, v43
	v_add_f32_e32 v43, -1.0, v42
	v_add_f32_e32 v44, 1.0, v42
	v_add_f32_e32 v45, 1.0, v43
	v_add_f32_e32 v46, -1.0, v44
	v_sub_f32_e32 v45, v42, v45
	v_sub_f32_e32 v42, v42, v46
	v_mul_f32_e32 v46, 0x3f317218, v40
	v_add_f32_e32 v45, v41, v45
	v_add_f32_e32 v41, v41, v42
	v_fma_f32 v42, v40, s39, -v46
	v_add_f32_e32 v47, v43, v45
	v_add_f32_e32 v48, v44, v41
	v_fmac_f32_e32 v42, 0xb102e308, v40
	v_sub_f32_e32 v40, v47, v43
	v_sub_f32_e32 v43, v48, v44
	v_rcp_f32_e32 v44, v48
	v_add_f32_e32 v49, v46, v42
	v_sub_f32_e32 v41, v41, v43
	v_sub_f32_e32 v43, v49, v46
	v_sub_f32_e32 v42, v42, v43
	v_mul_f32_e32 v43, v47, v44
	v_sub_f32_e32 v40, v45, v40
	v_mul_f32_e32 v45, v48, v43
	v_fma_f32 v46, v43, v48, -v45
	v_fmac_f32_e32 v46, v43, v41
	v_add_f32_e32 v50, v45, v46
	v_sub_f32_e32 v51, v47, v50
	v_sub_f32_e32 v45, v50, v45
	v_sub_f32_e32 v47, v47, v51
	v_sub_f32_e32 v45, v45, v46
	v_sub_f32_e32 v46, v47, v50
	v_add_f32_e32 v40, v40, v46
	v_add_f32_e32 v40, v45, v40
	v_add_f32_e32 v45, v51, v40
	v_mul_f32_e32 v46, v44, v45
	v_sub_f32_e32 v47, v51, v45
	v_mul_f32_e32 v50, v48, v46
	v_add_f32_e32 v40, v40, v47
	v_add_f32_e32 v47, v43, v46
	v_fma_f32 v48, v46, v48, -v50
	v_sub_f32_e32 v43, v47, v43
	v_fmac_f32_e32 v48, v46, v41
	v_sub_f32_e32 v41, v46, v43
	v_add_f32_e32 v43, v50, v48
	v_sub_f32_e32 v46, v43, v50
	v_sub_f32_e32 v50, v45, v43
	v_sub_f32_e32 v45, v45, v50
	v_sub_f32_e32 v43, v45, v43
	v_sub_f32_e32 v46, v46, v48
	v_add_f32_e32 v40, v40, v43
	v_add_f32_e32 v40, v46, v40
	v_add_f32_e32 v40, v50, v40
	v_mul_f32_e32 v40, v44, v40
	v_add_f32_e32 v40, v41, v40
	v_add_f32_e32 v41, v47, v40
	v_mul_f32_e32 v43, v41, v41
	v_fmamk_f32 v46, v43, 0x3e9b6dac, v13
	v_sub_f32_e32 v44, v41, v47
	v_ldexp_f32 v45, v41, 1
	v_mul_f32_e32 v41, v41, v43
	v_fmaak_f32 v43, v43, v46, 0x3f2aaada
	v_mul_f32_e32 v41, v41, v43
	v_add_f32_e32 v43, v45, v41
	v_sub_f32_e32 v40, v40, v44
	v_sub_f32_e32 v44, v43, v45
	v_ldexp_f32 v40, v40, 1
	v_sub_f32_e32 v41, v41, v44
	v_add_f32_e32 v40, v40, v41
	v_add_f32_e32 v41, v43, v40
	v_sub_f32_e32 v43, v41, v43
	v_add_f32_e32 v44, v49, v41
	v_sub_f32_e32 v40, v40, v43
	v_sub_f32_e32 v43, v44, v49
	v_sub_f32_e32 v45, v44, v43
	v_sub_f32_e32 v41, v41, v43
	v_add_f32_e32 v43, v42, v40
	v_sub_f32_e32 v45, v49, v45
	v_sub_f32_e32 v46, v43, v42
	v_add_f32_e32 v41, v41, v45
	v_sub_f32_e32 v45, v43, v46
	v_sub_f32_e32 v40, v40, v46
	v_sub_f32_e32 v42, v42, v45
	v_add_f32_e32 v41, v43, v41
	v_add_f32_e32 v40, v40, v42
	v_add_f32_e32 v42, v44, v41
	v_sub_f32_e32 v43, v42, v44
	v_sub_f32_e32 v41, v41, v43
	v_add_f32_e32 v40, v40, v41
	v_add_f32_e32 v40, v42, v40
	v_cmp_neq_f32_e32 vcc, s40, v5
	s_nop 1
	v_cndmask_b32_e32 v40, v29, v40, vcc
	v_cmp_ngt_f32_e32 vcc, -1.0, v5
	s_nop 1
	v_cndmask_b32_e32 v40, v30, v40, vcc
	v_cmp_neq_f32_e32 vcc, -1.0, v5
	s_nop 1
	v_cndmask_b32_e32 v40, v31, v40, vcc
	v_cmp_lt_f32_e64 vcc, |v5|, s41
	s_nop 1
	v_cndmask_b32_e32 v5, v40, v5, vcc
	v_sub_f32_e32 v0, v0, v5
	v_cmp_lt_i32_e32 vcc, v18, v15
	s_nop 0
	v_add_f32_dpp v0, v0, v0 row_shr:1 row_mask:0xf bank_mask:0xf bound_ctrl:1
	s_nop 1
	v_add_f32_dpp v0, v0, v0 row_shr:2 row_mask:0xf bank_mask:0xf bound_ctrl:1
	s_nop 1
	v_add_f32_dpp v0, v0, v0 row_shr:4 row_mask:0xf bank_mask:0xf bound_ctrl:1
	s_nop 1
	v_add_f32_dpp v0, v0, v0 row_shr:8 row_mask:0xf bank_mask:0xf bound_ctrl:1
	s_nop 1
	v_mov_b32_dpp v37, v0 row_bcast:15 row_mask:0xa bank_mask:0xf
	v_add_f32_e32 v5, v0, v37
	v_cndmask_b32_e32 v37, v14, v18, vcc
	v_lshlrev_b32_e32 v37, 2, v37
	v_mov_b32_dpp v39, v5 row_bcast:31 row_mask:0xc bank_mask:0xf
	s_waitcnt vmcnt(0)
; __device__ __forceinline__ bf16_t f2bf(float f) { return (bf16_t)(cvt_pk_bf16(f, 0.f) & 0xffffu); }
; __device__ __forceinline__ bf16_t f2bf_sw(float f) { const unsigned u = __float_as_uint(f); return (bf16_t)((u + 0x7fffu + ((u >> 16) & 1u)) >> 16); }
; __device__ __forceinline__ void phase_mlstm_a(const Args& a, unsigned char* lds) {
;     ...
;             const float bl = __shfl(bs, 63);
;             const float wk = bl - bs + ig;
;             const float ml = wave_max(wk);
;             WS_[lane] = __expf(wk - ml);
;             if (lane == 0) { ML[item] = ml; BL[item] = bl; }
;         }
;         for (int i = tid; i < 1024; i += 512) { const int s = i >> 4, d0 = (i & 15) * 8; float f[8]; unpack8(*(const u32x4*)(P + (r0 + s) * LDP + C_MV + h * 128 + d0), f);
; #pragma unroll
;             for (int e = 0; e < 8; ++e) VT[(d0 + e) * 72 + s] = f2bf(f[e]); }
;         __syncthreads();
;         { const int s = tid >> 3, d0 = (tid & 7) * 8; float f[8]; unpack8(*(const u32x4*)(QK + (r0 + s) * 512 + 256 + h * 64 + d0), f); const float w = WS_[s];
; #pragma unroll
;             for (int e = 0; e < 8; ++e) KT[(d0 + e) * 72 + s] = f2bf(f[e] * w); }
;         __syncthreads();
;         bf16_t* st = ST + (size_t)item * 8192;
; #pragma unroll
;         for (int nt = 0; nt < 4; ++nt) {
;             const f32x4 acc = mma_lds(VT + wave * 16 * 72, 72, KT + nt * 16 * 72, 72, 64, lane);
; #pragma unroll
;             for (int j = 0; j < 4; ++j) st[(wave * 16 + (lane >> 4) * 4 + j) * 64 + nt * 16 + (lane & 15)] = f2bf_sw(acc[j]);
	v_pk_add_f32 v[4:5], v[4:5], v[38:39]
	ds_bpermute_b32 v0, v35, v5
	v_cmp_lt_i32_e32 vcc, v19, v15
	s_waitcnt lgkmcnt(0)
	v_sub_f32_e32 v5, v0, v5
	v_add_f32_e32 v5, v4, v5
	ds_bpermute_b32 v4, v37, v5
	v_cndmask_b32_e32 v37, v14, v19, vcc
	v_lshlrev_b32_e32 v37, 2, v37
	v_cmp_lt_i32_e32 vcc, v20, v15
	s_waitcnt lgkmcnt(0)
	v_max_f32_e32 v4, v4, v4
	v_max_f32_e32 v4, v5, v4
	ds_bpermute_b32 v37, v37, v4
	v_cndmask_b32_e32 v38, v14, v20, vcc
	v_lshlrev_b32_e32 v38, 2, v38
	v_cmp_lt_i32_e32 vcc, v21, v15
	s_waitcnt lgkmcnt(0)
	v_max_f32_e32 v37, v37, v37
	v_max_f32_e32 v4, v4, v37
	ds_bpermute_b32 v37, v38, v4
	v_cndmask_b32_e32 v38, v14, v21, vcc
	v_lshlrev_b32_e32 v38, 2, v38
	v_cmp_lt_i32_e32 vcc, v22, v15
	s_waitcnt lgkmcnt(0)
	v_max_f32_e32 v37, v37, v37
	v_max_f32_e32 v4, v4, v37
	ds_bpermute_b32 v37, v38, v4
	v_cndmask_b32_e32 v38, v14, v22, vcc
	v_lshlrev_b32_e32 v38, 2, v38
	v_cmp_lt_i32_e32 vcc, v36, v15
	s_waitcnt lgkmcnt(0)
	v_max_f32_e32 v37, v37, v37
	v_max_f32_e32 v4, v4, v37
	ds_bpermute_b32 v37, v38, v4
	v_cndmask_b32_e32 v38, v14, v36, vcc
	s_waitcnt lgkmcnt(0)
	v_max_f32_e32 v37, v37, v37
	v_max_f32_e32 v4, v4, v37
	v_lshlrev_b32_e32 v37, 2, v38
	ds_bpermute_b32 v37, v37, v4
	s_waitcnt lgkmcnt(0)
	v_max_f32_e32 v37, v37, v37
	v_max_f32_e32 v4, v4, v37
	v_sub_f32_e32 v5, v5, v4
	v_mul_f32_e32 v5, 0x3fb8aa3b, v5
	v_exp_f32_e32 v5, v5
	ds_write_b32 v6, v5 offset:27648
	s_and_b64 exec, exec, s[6:7]
	s_cbranch_execz .LBB0_659
	s_ashr_i32 s15, s14, 31
	s_lshl_b64 s[62:63], s[14:15], 2
	s_add_u32 s64, s22, s62
	s_addc_u32 s65, s23, s63
	s_add_u32 s62, s24, s62
	s_addc_u32 s63, s25, s63
	global_store_dword v1, v4, s[64:65]
	global_store_dword v1, v0, s[62:63]
.LBB0_659:
	s_or_b64 exec, exec, s[20:21]
	v_and_b32_e32 v39, 0x78, v162
	v_mad_u32_u24 v39, v39, s26, v12
	s_waitcnt vmcnt(2)
	ds_write_b16 v39, v228
	ds_write_b16_d16_hi v39, v228 offset:144
	ds_write_b16 v39, v229 offset:288
	ds_write_b16_d16_hi v39, v229 offset:432
	ds_write_b16 v39, v230 offset:576
	ds_write_b16_d16_hi v39, v230 offset:720
	ds_write_b16 v39, v231 offset:864
	ds_write_b16_d16_hi v39, v231 offset:1008
	s_waitcnt vmcnt(1)
	ds_write_b16 v39, v232 offset:64
	ds_write_b16_d16_hi v39, v232 offset:208
	ds_write_b16 v39, v233 offset:352
	ds_write_b16_d16_hi v39, v233 offset:496
	ds_write_b16 v39, v234 offset:640
	ds_write_b16_d16_hi v39, v234 offset:784
	ds_write_b16 v39, v235 offset:928
	ds_write_b16_d16_hi v39, v235 offset:1072
	s_waitcnt lgkmcnt(0)
	s_barrier
	ds_read_b32 v0, v7 offset:27648
	s_ashr_i32 s15, s14, 31
	s_lshl_b64 s[16:17], s[14:15], 14
	s_add_u32 s16, s46, s16
	s_addc_u32 s17, s47, s17
	s_waitcnt vmcnt(0)
	v_mov_b32_e32 v38, v236
	v_mov_b32_e32 v39, v237
	v_mov_b32_e32 v40, v238
	v_mov_b32_e32 v41, v239
	v_lshlrev_b32_e32 v4, 16, v38
	s_waitcnt lgkmcnt(0)
	v_mul_f32_e32 v4, v0, v4
	v_and_b32_e32 v5, 0xffff0000, v38
	v_cvt_pk_bf16_f32 v4, v4, v1
	v_lshlrev_b32_e32 v37, 16, v39
	v_mul_f32_e32 v5, v0, v5
	ds_write_b16 v23, v4 offset:18432
	v_cvt_pk_bf16_f32 v4, v5, v1
	v_and_b32_e32 v38, 0xffff0000, v39
	v_mul_f32_e32 v37, v0, v37
	ds_write_b16 v23, v4 offset:18576
	v_cvt_pk_bf16_f32 v4, v37, v1
	v_lshlrev_b32_e32 v39, 16, v40
	v_mul_f32_e32 v38, v0, v38
	ds_write_b16 v23, v4 offset:18720
	v_cvt_pk_bf16_f32 v4, v38, v1
	v_and_b32_e32 v40, 0xffff0000, v40
	v_lshlrev_b32_e32 v42, 16, v41
	v_and_b32_e32 v41, 0xffff0000, v41
	v_mul_f32_e32 v39, v0, v39
	ds_write_b16 v23, v4 offset:18864
	v_cvt_pk_bf16_f32 v4, v39, v1
	v_mul_f32_e32 v40, v0, v40
	v_mul_f32_e32 v42, v0, v42
	v_mul_f32_e32 v0, v0, v41
	ds_write_b16 v23, v4 offset:19008
	v_cvt_pk_bf16_f32 v4, v40, v1
	ds_write_b16 v23, v4 offset:19152
	v_cvt_pk_bf16_f32 v4, v42, v1
	ds_write_b16 v23, v4 offset:19296
	v_cvt_pk_bf16_f32 v0, v0, v1
	ds_write_b16 v23, v0 offset:19440
	s_waitcnt lgkmcnt(0)
	s_barrier
	ds_read_b128 v[38:41], v9
	ds_read_b128 v[42:45], v8 offset:18432
	ds_read_b128 v[46:49], v9 offset:64
	ds_read_b128 v[50:53], v8 offset:18496
	ds_read_b128 v[54:57], v8 offset:20736
	ds_read_b128 v[58:61], v8 offset:20800
	ds_read_b128 v[62:65], v8 offset:23040
	ds_read_b128 v[66:69], v8 offset:23104
	ds_read_b128 v[70:73], v8 offset:25344
	ds_read_b128 v[74:77], v8 offset:25408
	s_waitcnt lgkmcnt(8)
	v_mfma_f32_16x16x32_bf16 v[42:45], v[38:41], v[42:45], 0
	s_waitcnt lgkmcnt(5)
	v_mfma_f32_16x16x32_bf16 v[54:57], v[38:41], v[54:57], 0
	s_waitcnt lgkmcnt(3)
	v_mfma_f32_16x16x32_bf16 v[62:65], v[38:41], v[62:65], 0
	s_waitcnt lgkmcnt(1)
	v_mfma_f32_16x16x32_bf16 v[38:41], v[38:41], v[70:73], 0
	v_mfma_f32_16x16x32_bf16 v[42:45], v[46:49], v[50:53], v[42:45]
	v_mfma_f32_16x16x32_bf16 v[50:53], v[46:49], v[58:61], v[54:57]
	v_mfma_f32_16x16x32_bf16 v[54:57], v[46:49], v[66:69], v[62:65]
	s_nop 5
	v_bfe_u32 v0, v42, 16, 1
	v_bfe_u32 v4, v43, 16, 1
	v_bfe_u32 v5, v44, 16, 1
	s_waitcnt lgkmcnt(0)
	v_mfma_f32_16x16x32_bf16 v[38:41], v[46:49], v[74:77], v[38:41]
	v_bfe_u32 v37, v45, 16, 1
	v_bfe_u32 v46, v50, 16, 1
	v_bfe_u32 v47, v51, 16, 1
	v_bfe_u32 v48, v52, 16, 1
	v_bfe_u32 v49, v53, 16, 1
	v_bfe_u32 v58, v54, 16, 1
	v_bfe_u32 v59, v55, 16, 1
	v_bfe_u32 v60, v56, 16, 1
	v_bfe_u32 v61, v57, 16, 1
	v_bfe_u32 v62, v38, 16, 1
	v_bfe_u32 v63, v39, 16, 1
	v_bfe_u32 v64, v40, 16, 1
	v_add3_u32 v0, v42, v0, s43
	v_add3_u32 v4, v43, v4, s43
	v_add3_u32 v5, v44, v5, s43
	v_add3_u32 v37, v45, v37, s43
	v_add3_u32 v42, v50, v46, s43
	v_add3_u32 v43, v51, v47, s43
	v_add3_u32 v44, v52, v48, s43
	v_add3_u32 v45, v53, v49, s43
	v_add3_u32 v46, v54, v58, s43
	v_add3_u32 v47, v55, v59, s43
	v_add3_u32 v48, v56, v60, s43
	v_add3_u32 v49, v57, v61, s43
	v_add3_u32 v38, v38, v62, s43
	v_add3_u32 v39, v39, v63, s43
	global_store_short_d16_hi v24, v0, s[16:17]
	global_store_short_d16_hi v24, v4, s[16:17] offset:128
	global_store_short_d16_hi v24, v5, s[16:17] offset:256
	global_store_short_d16_hi v25, v37, s[16:17]
	global_store_short_d16_hi v24, v42, s[16:17] offset:32
	global_store_short_d16_hi v26, v43, s[16:17] offset:128
	global_store_short_d16_hi v26, v44, s[16:17] offset:256
	global_store_short_d16_hi v25, v45, s[16:17] offset:32
	global_store_short_d16_hi v24, v46, s[16:17] offset:64
	global_store_short_d16_hi v27, v47, s[16:17] offset:128
	global_store_short_d16_hi v27, v48, s[16:17] offset:256
	global_store_short_d16_hi v25, v49, s[16:17] offset:64
	global_store_short_d16_hi v24, v38, s[16:17] offset:96
	global_store_short_d16_hi v28, v39, s[16:17] offset:128
	v_add3_u32 v0, v40, v64, s43
	global_store_short_d16_hi v28, v0, s[16:17] offset:256
	v_bfe_u32 v0, v41, 16, 1
	v_add3_u32 v0, v41, v0, s43
	global_store_short_d16_hi v25, v0, s[16:17] offset:96
	s_and_saveexec_b64 s[16:17], s[4:5]
	s_cbranch_execz .LBB0_655
; __device__ __forceinline__ float bf1(bf16_t u) { return __uint_as_float(((unsigned)u) << 16); }
; __device__ __forceinline__ void phase_mlstm_a(const Args& a, unsigned char* lds) {
;     ...
;         if (tid < 64) { float s = 0.f; for (int k = 0; k < 64; ++k) s += bf1(KT[tid * 72 + k]); DN[item * 64 + tid] = s; }
	ds_read_b128 v[38:41], v10 offset:18432
	ds_read_b128 v[42:45], v10 offset:18448
	ds_read_b128 v[46:49], v10 offset:18464
	ds_read_b128 v[50:53], v10 offset:18480
	s_waitcnt lgkmcnt(3)
	v_lshlrev_b32_e32 v0, 16, v38
	v_and_b32_e32 v4, 0xffff0000, v38
	v_add_f32_e32 v0, 0, v0
	v_add_f32_e32 v0, v0, v4
	v_lshlrev_b32_e32 v4, 16, v39
	v_add_f32_e32 v0, v0, v4
	v_and_b32_e32 v4, 0xffff0000, v39
	v_add_f32_e32 v0, v0, v4
	v_lshlrev_b32_e32 v4, 16, v40
	v_add_f32_e32 v0, v0, v4
	v_and_b32_e32 v4, 0xffff0000, v40
	v_add_f32_e32 v0, v0, v4
	v_lshlrev_b32_e32 v4, 16, v41
	v_add_f32_e32 v0, v0, v4
	v_and_b32_e32 v4, 0xffff0000, v41
	v_add_f32_e32 v0, v0, v4
	s_waitcnt lgkmcnt(2)
	v_lshlrev_b32_e32 v4, 16, v42
	v_add_f32_e32 v0, v0, v4
	v_and_b32_e32 v4, 0xffff0000, v42
	v_add_f32_e32 v0, v0, v4
	v_lshlrev_b32_e32 v4, 16, v43
	v_add_f32_e32 v0, v0, v4
	v_and_b32_e32 v4, 0xffff0000, v43
	v_add_f32_e32 v0, v0, v4
	v_lshlrev_b32_e32 v4, 16, v44
	v_add_f32_e32 v0, v0, v4
	v_and_b32_e32 v4, 0xffff0000, v44
	v_add_f32_e32 v0, v0, v4
	v_lshlrev_b32_e32 v4, 16, v45
	v_add_f32_e32 v0, v0, v4
	v_and_b32_e32 v4, 0xffff0000, v45
	v_add_f32_e32 v0, v0, v4
	s_waitcnt lgkmcnt(1)
	v_lshlrev_b32_e32 v4, 16, v46
	v_add_f32_e32 v0, v0, v4
	v_and_b32_e32 v4, 0xffff0000, v46
	v_add_f32_e32 v0, v0, v4
	v_lshlrev_b32_e32 v4, 16, v47
	v_add_f32_e32 v0, v0, v4
	v_and_b32_e32 v4, 0xffff0000, v47
	v_add_f32_e32 v0, v0, v4
	v_lshlrev_b32_e32 v4, 16, v48
	v_add_f32_e32 v0, v0, v4
	v_and_b32_e32 v4, 0xffff0000, v48
	v_add_f32_e32 v0, v0, v4
	v_lshlrev_b32_e32 v4, 16, v49
	v_add_f32_e32 v0, v0, v4
	v_and_b32_e32 v4, 0xffff0000, v49
	v_add_f32_e32 v0, v0, v4
	s_waitcnt lgkmcnt(0)
	v_lshlrev_b32_e32 v4, 16, v50
	v_add_f32_e32 v0, v0, v4
	v_and_b32_e32 v4, 0xffff0000, v50
	v_add_f32_e32 v0, v0, v4
	v_lshlrev_b32_e32 v4, 16, v51
	v_add_f32_e32 v0, v0, v4
	v_and_b32_e32 v4, 0xffff0000, v51
	ds_read_b128 v[38:41], v10 offset:18496
	ds_read_b128 v[42:45], v10 offset:18512
	v_add_f32_e32 v0, v0, v4
	v_lshlrev_b32_e32 v4, 16, v52
	v_add_f32_e32 v0, v0, v4
	v_and_b32_e32 v4, 0xffff0000, v52
	v_add_f32_e32 v0, v0, v4
	v_lshlrev_b32_e32 v4, 16, v53
	v_add_f32_e32 v0, v0, v4
	v_and_b32_e32 v4, 0xffff0000, v53
	v_add_f32_e32 v0, v0, v4
	s_waitcnt lgkmcnt(1)
	v_lshlrev_b32_e32 v4, 16, v38
	v_add_f32_e32 v0, v0, v4
	v_and_b32_e32 v4, 0xffff0000, v38
	v_add_f32_e32 v0, v0, v4
	v_lshlrev_b32_e32 v4, 16, v39
	v_add_f32_e32 v0, v0, v4
	v_and_b32_e32 v4, 0xffff0000, v39
	v_add_f32_e32 v0, v0, v4
	v_lshlrev_b32_e32 v4, 16, v40
	v_add_f32_e32 v0, v0, v4
	v_and_b32_e32 v4, 0xffff0000, v40
	v_add_f32_e32 v0, v0, v4
	v_lshlrev_b32_e32 v4, 16, v41
	v_add_f32_e32 v0, v0, v4
	v_and_b32_e32 v4, 0xffff0000, v41
	v_add_f32_e32 v0, v0, v4
	s_waitcnt lgkmcnt(0)
	v_lshlrev_b32_e32 v4, 16, v42
	v_add_f32_e32 v0, v0, v4
	v_and_b32_e32 v4, 0xffff0000, v42
	v_add_f32_e32 v0, v0, v4
	v_lshlrev_b32_e32 v4, 16, v43
	v_add_f32_e32 v0, v0, v4
	v_and_b32_e32 v4, 0xffff0000, v43
	ds_read_b128 v[38:41], v10 offset:18528
	v_add_f32_e32 v0, v0, v4
	v_lshlrev_b32_e32 v4, 16, v44
	v_add_f32_e32 v0, v0, v4
	v_and_b32_e32 v4, 0xffff0000, v44
	v_add_f32_e32 v0, v0, v4
	v_lshlrev_b32_e32 v4, 16, v45
	v_add_f32_e32 v0, v0, v4
	v_and_b32_e32 v4, 0xffff0000, v45
	v_add_f32_e32 v0, v0, v4
	ds_read_b128 v[42:45], v10 offset:18544
	s_waitcnt lgkmcnt(1)
	v_lshlrev_b32_e32 v4, 16, v38
	v_add_f32_e32 v0, v0, v4
	v_and_b32_e32 v4, 0xffff0000, v38
	v_add_f32_e32 v0, v0, v4
	v_lshlrev_b32_e32 v4, 16, v39
	v_add_f32_e32 v0, v0, v4
	v_and_b32_e32 v4, 0xffff0000, v39
	v_add_f32_e32 v0, v0, v4
	v_lshlrev_b32_e32 v4, 16, v40
	v_add_f32_e32 v0, v0, v4
	v_and_b32_e32 v4, 0xffff0000, v40
	v_add_f32_e32 v0, v0, v4
	v_lshlrev_b32_e32 v4, 16, v41
	v_add_f32_e32 v0, v0, v4
	v_and_b32_e32 v4, 0xffff0000, v41
	v_add_f32_e32 v0, v0, v4
	s_waitcnt lgkmcnt(0)
	v_lshlrev_b32_e32 v4, 16, v42
	v_add_f32_e32 v0, v0, v4
	v_and_b32_e32 v4, 0xffff0000, v42
	v_add_f32_e32 v0, v0, v4
	v_lshlrev_b32_e32 v4, 16, v43
	v_add_f32_e32 v0, v0, v4
	v_and_b32_e32 v4, 0xffff0000, v43
	v_add_f32_e32 v0, v0, v4
	v_lshlrev_b32_e32 v4, 16, v44
	v_add_f32_e32 v0, v0, v4
	v_and_b32_e32 v4, 0xffff0000, v44
	v_add_f32_e32 v0, v0, v4
	v_lshlrev_b32_e32 v4, 16, v45
	v_add_f32_e32 v0, v0, v4
	v_and_b32_e32 v4, 0xffff0000, v45
	v_add_f32_e32 v0, v0, v4
	v_or_b32_e32 v4, s60, v156
	v_ashrrev_i32_e32 v5, 31, v4
	v_lshl_add_u64 v[4:5], v[4:5], 2, s[36:37]
	global_store_dword v[4:5], v0, off
	s_branch .LBB0_655
